# speedup vs baseline: 1.0787x; 1.0071x over previous
.Lmy_bias_done:
	s_nop 1
	s_waitcnt lgkmcnt(7)
	v_mfma_f32_32x32x16_bf16 v[80:95], v[176:179], v[112:115], v[80:95]
	s_waitcnt lgkmcnt(6)
	v_mfma_f32_32x32x16_bf16 v[96:111], v[180:183], v[112:115], v[96:111]
	s_waitcnt lgkmcnt(5)
	v_mfma_f32_32x32x16_bf16 v[80:95], v[184:187], v[116:119], v[80:95]
	s_waitcnt lgkmcnt(4)
	v_mfma_f32_32x32x16_bf16 v[96:111], v[196:199], v[116:119], v[96:111]
	s_waitcnt lgkmcnt(3)
	v_mfma_f32_32x32x16_bf16 v[80:95], v[200:203], v[120:123], v[80:95]
	s_waitcnt lgkmcnt(2)
	v_mfma_f32_32x32x16_bf16 v[96:111], v[204:207], v[120:123], v[96:111]
	s_waitcnt lgkmcnt(1)
	v_mfma_f32_32x32x16_bf16 v[80:95], v[244:247], v[124:127], v[80:95]
	s_waitcnt lgkmcnt(0)
	v_mfma_f32_32x32x16_bf16 v[96:111], v[248:251], v[124:127], v[96:111]
	v_add_u32_e32 v0, v14, v152
	ds_read_b128 v[176:179], v0
	ds_read_b128 v[180:183], v0 offset:8704
	ds_read_b128 v[184:187], v0 offset:17408
	ds_read_b128 v[196:199], v0 offset:26112
	ds_read_b128 v[200:203], v0 offset:32
	ds_read_b128 v[204:207], v0 offset:8736
	ds_read_b128 v[244:247], v0 offset:17440
	ds_read_b128 v[248:251], v0 offset:26144
	v_cmp_gt_i32_e32 vcc, v144, v233
	s_and_saveexec_b64 s[98:99], vcc
	s_cbranch_execz .LBB0_227
	v_cmp_lt_i32_e64 s[72:73], 26, v243
	v_cmp_lt_i32_e64 s[74:75], 27, v243
	v_cmp_lt_i32_e64 s[70:71], 25, v243
	s_or_b64 s[72:73], s[74:75], s[72:73]
	v_cmp_lt_i32_e64 s[68:69], 24, v243
	s_or_b64 s[70:71], s[72:73], s[70:71]
	v_cmp_lt_i32_e64 s[66:67], 19, v243
	s_or_b64 s[68:69], s[70:71], s[68:69]
	v_cmp_lt_i32_e64 s[64:65], 18, v243
	s_or_b64 s[66:67], s[68:69], s[66:67]
	v_cmp_lt_i32_e64 s[62:63], 17, v243
	s_or_b64 s[64:65], s[66:67], s[64:65]
	v_cmp_lt_i32_e64 s[60:61], 16, v243
	s_or_b64 s[62:63], s[64:65], s[62:63]
	v_cmp_lt_i32_e64 s[58:59], 11, v243
	s_or_b64 s[60:61], s[62:63], s[60:61]
	v_cmp_lt_i32_e64 s[56:57], 10, v243
	s_or_b64 s[58:59], s[60:61], s[58:59]
	v_cmp_lt_i32_e64 s[54:55], 9, v243
	s_or_b64 s[56:57], s[58:59], s[56:57]
	v_cmp_lt_i32_e64 s[52:53], 8, v243
	s_or_b64 s[54:55], s[56:57], s[54:55]
	v_cmp_lt_i32_e64 s[50:51], 3, v243
	s_or_b64 s[52:53], s[54:55], s[52:53]
	v_cmp_lt_i32_e64 s[48:49], 2, v243
	s_or_b64 s[50:51], s[52:53], s[50:51]
	v_cmp_lt_i32_e64 s[46:47], 1, v243
	s_or_b64 s[48:49], s[50:51], s[48:49]
	v_cmp_lt_i32_e64 s[44:45], 0, v243
	s_or_b64 s[46:47], s[48:49], s[46:47]
	s_or_b64 s[44:45], s[46:47], s[44:45]
	v_cmp_lt_i32_e64 s[40:41], 58, v243
	v_cndmask_b32_e64 v80, v209, v80, s[44:45]
	v_cmp_lt_i32_e64 s[44:45], 59, v243
	v_cmp_lt_i32_e64 s[38:39], 57, v243
	s_or_b64 s[40:41], s[44:45], s[40:41]
	v_cmp_lt_i32_e64 s[36:37], 56, v243
	s_or_b64 s[38:39], s[40:41], s[38:39]
	v_cmp_lt_i32_e64 s[34:35], 51, v243
	s_or_b64 s[36:37], s[38:39], s[36:37]
	v_cmp_lt_i32_e64 s[30:31], 50, v243
	s_or_b64 s[34:35], s[36:37], s[34:35]
	v_cmp_lt_i32_e64 s[28:29], 49, v243
	s_or_b64 s[30:31], s[34:35], s[30:31]
	v_cmp_lt_i32_e64 s[26:27], 48, v243
	s_or_b64 s[28:29], s[30:31], s[28:29]
	v_cmp_lt_i32_e64 s[24:25], 43, v243
	s_or_b64 s[26:27], s[28:29], s[26:27]
	v_cmp_lt_i32_e64 s[22:23], 42, v243
	s_or_b64 s[24:25], s[26:27], s[24:25]
	v_cmp_lt_i32_e64 s[20:21], 41, v243
	s_or_b64 s[22:23], s[24:25], s[22:23]
	v_cmp_lt_i32_e64 s[18:19], 40, v243
	s_or_b64 s[20:21], s[22:23], s[20:21]
	v_cmp_lt_i32_e64 s[16:17], 35, v243
	s_or_b64 s[18:19], s[20:21], s[18:19]
	v_cmp_lt_i32_e64 s[14:15], 34, v243
	s_or_b64 s[16:17], s[18:19], s[16:17]
	v_cmp_lt_i32_e64 s[12:13], 33, v243
	s_or_b64 s[14:15], s[16:17], s[14:15]
	v_cmp_lt_i32_e32 vcc, 32, v243
	s_or_b64 s[12:13], s[14:15], s[12:13]
	s_or_b64 vcc, s[12:13], vcc
	v_cndmask_b32_e64 v95, v209, v95, s[74:75]
	v_cndmask_b32_e64 v94, v209, v94, s[72:73]
	v_cndmask_b32_e64 v93, v209, v93, s[70:71]
	v_cndmask_b32_e64 v92, v209, v92, s[68:69]
	v_cndmask_b32_e64 v91, v209, v91, s[66:67]
	v_cndmask_b32_e64 v90, v209, v90, s[64:65]
	v_cndmask_b32_e64 v89, v209, v89, s[62:63]
	v_cndmask_b32_e64 v88, v209, v88, s[60:61]
	v_cndmask_b32_e64 v87, v209, v87, s[58:59]
	v_cndmask_b32_e64 v86, v209, v86, s[56:57]
	v_cndmask_b32_e64 v85, v209, v85, s[54:55]
	v_cndmask_b32_e64 v84, v209, v84, s[52:53]
	v_cndmask_b32_e64 v83, v209, v83, s[50:51]
	s_movk_i32 s51, 0x7fff
	s_movk_i32 s50, 0x1080
	v_cndmask_b32_e64 v82, v209, v82, s[48:49]
	s_mov_b32 s49, 0xee00000
	s_mov_b32 s3, s2
	s_mov_b32 s48, s85
	v_cndmask_b32_e64 v81, v209, v81, s[46:47]
	v_cndmask_b32_e64 v111, v209, v111, s[44:45]
	v_cndmask_b32_e64 v110, v209, v110, s[40:41]
	v_cndmask_b32_e64 v109, v209, v109, s[38:39]
	v_cndmask_b32_e64 v108, v209, v108, s[36:37]
	v_cndmask_b32_e64 v107, v209, v107, s[34:35]
	v_cndmask_b32_e64 v106, v209, v106, s[30:31]
	v_cndmask_b32_e64 v105, v209, v105, s[28:29]
	v_cndmask_b32_e64 v104, v209, v104, s[26:27]
	v_cndmask_b32_e64 v103, v209, v103, s[24:25]
	v_cndmask_b32_e64 v102, v209, v102, s[22:23]
	v_cndmask_b32_e64 v101, v209, v101, s[20:21]
	v_cndmask_b32_e64 v100, v209, v100, s[18:19]
	v_cndmask_b32_e64 v99, v209, v99, s[16:17]
	v_cndmask_b32_e64 v98, v209, v98, s[14:15]
	v_cndmask_b32_e64 v97, v209, v97, s[12:13]
	v_cndmask_b32_e32 v96, v209, v96, vcc
.LBB0_227:
	s_or_b64 exec, exec, s[98:99]
	s_nop 1
	v_max3_f32 v0, v80, v81, v82
	v_max3_f32 v188, v83, v84, v85
	v_max3_f32 v0, v0, v86, v87
	v_max3_f32 v188, v188, v88, v89
	v_max3_f32 v0, v0, v90, v91
	v_max3_f32 v188, v188, v92, v93
	v_max3_f32 v0, v0, v94, v95
	v_max3_f32 v188, v188, v96, v97
	v_max3_f32 v0, v0, v98, v99
	v_max3_f32 v188, v188, v100, v101
	v_max3_f32 v0, v0, v102, v103
	v_max3_f32 v188, v188, v104, v105
	v_max3_f32 v0, v0, v106, v107
	v_max3_f32 v188, v188, v108, v109
	v_max3_f32 v0, v0, v110, v111
	v_max_f32_e32 v0, v0, v188
	s_mov_b32 s12, 0x41000000
	v_cmp_lt_f32_e32 vcc, s12, v0
	s_cbranch_vccz .LBB0_229
	v_mov_b32_e32 v188, v0
	s_nop 1
	v_permlane32_swap_b32_e32 v0, v188
	v_max_f32_e32 v0, v0, v188
	v_max_f32_e32 v0, 0, v0
	v_exp_f32_e64 v188, -v0
	s_nop 0
	v_pk_mul_f32 v[78:79], v[78:79], v[188:189] op_sel_hi:[1,0]
	v_pk_mul_f32 v[76:77], v[76:77], v[188:189] op_sel_hi:[1,0]
	v_pk_mul_f32 v[74:75], v[74:75], v[188:189] op_sel_hi:[1,0]
	v_pk_mul_f32 v[72:73], v[72:73], v[188:189] op_sel_hi:[1,0]
	v_pk_mul_f32 v[70:71], v[70:71], v[188:189] op_sel_hi:[1,0]
	v_pk_mul_f32 v[68:69], v[68:69], v[188:189] op_sel_hi:[1,0]
	v_pk_mul_f32 v[66:67], v[66:67], v[188:189] op_sel_hi:[1,0]
	v_pk_mul_f32 v[64:65], v[64:65], v[188:189] op_sel_hi:[1,0]
	v_pk_mul_f32 v[62:63], v[62:63], v[188:189] op_sel_hi:[1,0]
	v_pk_mul_f32 v[60:61], v[60:61], v[188:189] op_sel_hi:[1,0]
	v_pk_mul_f32 v[58:59], v[58:59], v[188:189] op_sel_hi:[1,0]
	v_pk_mul_f32 v[56:57], v[56:57], v[188:189] op_sel_hi:[1,0]
	v_pk_mul_f32 v[54:55], v[54:55], v[188:189] op_sel_hi:[1,0]
	v_pk_mul_f32 v[52:53], v[52:53], v[188:189] op_sel_hi:[1,0]
	v_pk_mul_f32 v[50:51], v[50:51], v[188:189] op_sel_hi:[1,0]
	v_pk_mul_f32 v[48:49], v[48:49], v[188:189] op_sel_hi:[1,0]
	v_pk_mul_f32 v[46:47], v[46:47], v[188:189] op_sel_hi:[1,0]
	v_pk_mul_f32 v[44:45], v[44:45], v[188:189] op_sel_hi:[1,0]
	v_pk_mul_f32 v[42:43], v[42:43], v[188:189] op_sel_hi:[1,0]
	v_pk_mul_f32 v[40:41], v[40:41], v[188:189] op_sel_hi:[1,0]
	v_pk_mul_f32 v[38:39], v[38:39], v[188:189] op_sel_hi:[1,0]
	v_pk_mul_f32 v[36:37], v[36:37], v[188:189] op_sel_hi:[1,0]
	v_pk_mul_f32 v[34:35], v[34:35], v[188:189] op_sel_hi:[1,0]
	v_pk_mul_f32 v[32:33], v[32:33], v[188:189] op_sel_hi:[1,0]
	v_pk_mul_f32 v[30:31], v[30:31], v[188:189] op_sel_hi:[1,0]
	v_pk_mul_f32 v[28:29], v[28:29], v[188:189] op_sel_hi:[1,0]
	v_pk_mul_f32 v[26:27], v[26:27], v[188:189] op_sel_hi:[1,0]
	v_pk_mul_f32 v[24:25], v[24:25], v[188:189] op_sel_hi:[1,0]
	v_pk_mul_f32 v[22:23], v[22:23], v[188:189] op_sel_hi:[1,0]
	v_pk_mul_f32 v[20:21], v[20:21], v[188:189] op_sel_hi:[1,0]
	v_pk_mul_f32 v[18:19], v[18:19], v[188:189] op_sel_hi:[1,0]
	v_pk_mul_f32 v[16:17], v[16:17], v[188:189] op_sel_hi:[1,0]
	v_mul_f32_e32 v224, v224, v188
	v_pk_add_f32 v[80:81], v[80:81], v[0:1] op_sel_hi:[1,0] neg_lo:[0,1] neg_hi:[0,1]
	v_pk_add_f32 v[82:83], v[82:83], v[0:1] op_sel_hi:[1,0] neg_lo:[0,1] neg_hi:[0,1]
	v_pk_add_f32 v[84:85], v[84:85], v[0:1] op_sel_hi:[1,0] neg_lo:[0,1] neg_hi:[0,1]
	v_pk_add_f32 v[86:87], v[86:87], v[0:1] op_sel_hi:[1,0] neg_lo:[0,1] neg_hi:[0,1]
	v_pk_add_f32 v[88:89], v[88:89], v[0:1] op_sel_hi:[1,0] neg_lo:[0,1] neg_hi:[0,1]
	v_pk_add_f32 v[90:91], v[90:91], v[0:1] op_sel_hi:[1,0] neg_lo:[0,1] neg_hi:[0,1]
	v_pk_add_f32 v[92:93], v[92:93], v[0:1] op_sel_hi:[1,0] neg_lo:[0,1] neg_hi:[0,1]
	v_pk_add_f32 v[94:95], v[94:95], v[0:1] op_sel_hi:[1,0] neg_lo:[0,1] neg_hi:[0,1]
	v_pk_add_f32 v[96:97], v[96:97], v[0:1] op_sel_hi:[1,0] neg_lo:[0,1] neg_hi:[0,1]
	v_pk_add_f32 v[98:99], v[98:99], v[0:1] op_sel_hi:[1,0] neg_lo:[0,1] neg_hi:[0,1]
	v_pk_add_f32 v[100:101], v[100:101], v[0:1] op_sel_hi:[1,0] neg_lo:[0,1] neg_hi:[0,1]
	v_pk_add_f32 v[102:103], v[102:103], v[0:1] op_sel_hi:[1,0] neg_lo:[0,1] neg_hi:[0,1]
	v_pk_add_f32 v[104:105], v[104:105], v[0:1] op_sel_hi:[1,0] neg_lo:[0,1] neg_hi:[0,1]
	v_pk_add_f32 v[106:107], v[106:107], v[0:1] op_sel_hi:[1,0] neg_lo:[0,1] neg_hi:[0,1]
	v_pk_add_f32 v[108:109], v[108:109], v[0:1] op_sel_hi:[1,0] neg_lo:[0,1] neg_hi:[0,1]
	v_pk_add_f32 v[110:111], v[110:111], v[0:1] op_sel_hi:[1,0] neg_lo:[0,1] neg_hi:[0,1]
	v_add_f32_e32 v2, v2, v0
.LBB0_229:
	v_add_u32_e32 v0, v14, v152
	v_exp_f32_e32 v80, v80
	v_exp_f32_e32 v81, v81
	v_exp_f32_e32 v82, v82
	v_exp_f32_e32 v83, v83
	v_exp_f32_e32 v84, v84
	v_exp_f32_e32 v85, v85
	v_exp_f32_e32 v86, v86
	v_exp_f32_e32 v87, v87
	v_pk_add_f32 v[188:189], v[80:81], v[82:83]
	v_cvt_pk_bf16_f32 v80, v80, v81
	v_cvt_pk_bf16_f32 v81, v82, v83
	v_cvt_pk_bf16_f32 v82, v84, v85
	v_cvt_pk_bf16_f32 v83, v86, v87
	v_pk_add_f32 v[188:189], v[188:189], v[84:85]
	v_pk_add_f32 v[188:189], v[188:189], v[86:87]
	s_waitcnt lgkmcnt(4)
	v_mfma_f32_32x32x16_bf16 v[64:79], v[176:179], v[80:83], v[64:79]
	v_exp_f32_e32 v88, v88
	v_exp_f32_e32 v89, v89
	v_exp_f32_e32 v90, v90
	v_mfma_f32_32x32x16_bf16 v[48:63], v[180:183], v[80:83], v[48:63]
	v_exp_f32_e32 v91, v91
	v_exp_f32_e32 v92, v92
	v_exp_f32_e32 v93, v93
	v_mfma_f32_32x32x16_bf16 v[32:47], v[184:187], v[80:83], v[32:47]
	v_exp_f32_e32 v94, v94
	v_exp_f32_e32 v95, v95
	v_pk_add_f32 v[188:189], v[188:189], v[88:89]
	v_pk_add_f32 v[188:189], v[188:189], v[90:91]
	v_mfma_f32_32x32x16_bf16 v[16:31], v[196:199], v[80:83], v[16:31]
	v_cvt_pk_bf16_f32 v88, v88, v89
	v_cvt_pk_bf16_f32 v89, v90, v91
	v_cvt_pk_bf16_f32 v90, v92, v93
	v_cvt_pk_bf16_f32 v91, v94, v95
	v_pk_add_f32 v[188:189], v[188:189], v[92:93]
	v_pk_add_f32 v[188:189], v[188:189], v[94:95]
	ds_read_b128 v[176:179], v0 offset:64
	ds_read_b128 v[180:183], v0 offset:8768
	ds_read_b128 v[184:187], v0 offset:17472
	ds_read_b128 v[196:199], v0 offset:26176
	s_waitcnt lgkmcnt(4)
	v_mfma_f32_32x32x16_bf16 v[64:79], v[200:203], v[88:91], v[64:79]
	v_exp_f32_e32 v96, v96
	v_exp_f32_e32 v97, v97
	v_exp_f32_e32 v98, v98
	v_mfma_f32_32x32x16_bf16 v[48:63], v[204:207], v[88:91], v[48:63]
	v_exp_f32_e32 v99, v99
	v_exp_f32_e32 v100, v100
	v_exp_f32_e32 v101, v101
	v_mfma_f32_32x32x16_bf16 v[32:47], v[244:247], v[88:91], v[32:47]
	v_exp_f32_e32 v102, v102
	v_exp_f32_e32 v103, v103
	v_pk_add_f32 v[188:189], v[188:189], v[96:97]
	v_pk_add_f32 v[188:189], v[188:189], v[98:99]
	v_mfma_f32_32x32x16_bf16 v[16:31], v[248:251], v[88:91], v[16:31]
	v_pk_add_f32 v[188:189], v[188:189], v[100:101]
	v_pk_add_f32 v[188:189], v[188:189], v[102:103]
	v_cvt_pk_bf16_f32 v84, v96, v97
	v_cvt_pk_bf16_f32 v85, v98, v99
	v_cvt_pk_bf16_f32 v86, v100, v101
	v_cvt_pk_bf16_f32 v87, v102, v103
	ds_read_b128 v[200:203], v0 offset:96
	ds_read_b128 v[204:207], v0 offset:8800
	ds_read_b128 v[244:247], v0 offset:17504
	ds_read_b128 v[248:251], v0 offset:26208
	s_waitcnt lgkmcnt(4)
	v_mfma_f32_32x32x16_bf16 v[64:79], v[176:179], v[84:87], v[64:79]
	v_exp_f32_e32 v104, v104
	v_exp_f32_e32 v105, v105
	v_exp_f32_e32 v106, v106
	v_mfma_f32_32x32x16_bf16 v[48:63], v[180:183], v[84:87], v[48:63]
	v_exp_f32_e32 v107, v107
	v_exp_f32_e32 v108, v108
	v_exp_f32_e32 v109, v109
	v_mfma_f32_32x32x16_bf16 v[32:47], v[184:187], v[84:87], v[32:47]
	v_exp_f32_e32 v110, v110
	v_exp_f32_e32 v111, v111
	v_pk_add_f32 v[188:189], v[188:189], v[104:105]
	v_pk_add_f32 v[188:189], v[188:189], v[106:107]
	v_mfma_f32_32x32x16_bf16 v[16:31], v[196:199], v[84:87], v[16:31]
	v_cvt_pk_bf16_f32 v92, v104, v105
	v_cvt_pk_bf16_f32 v93, v106, v107
	v_cvt_pk_bf16_f32 v94, v108, v109
	v_cvt_pk_bf16_f32 v95, v110, v111
	v_pk_add_f32 v[188:189], v[188:189], v[108:109]
	v_pk_add_f32 v[188:189], v[188:189], v[110:111]
	s_waitcnt lgkmcnt(0)
	v_mfma_f32_32x32x16_bf16 v[64:79], v[200:203], v[92:95], v[64:79]
	v_mfma_f32_32x32x16_bf16 v[48:63], v[204:207], v[92:95], v[48:63]
	v_add_f32_e32 v0, v188, v189
	v_mfma_f32_32x32x16_bf16 v[32:47], v[244:247], v[92:95], v[32:47]
	v_add_f32_e32 v224, v224, v0
	v_mfma_f32_32x32x16_bf16 v[16:31], v[248:251], v[92:95], v[16:31]
